# P0: layer 0's w_in tiles transposed by a hand-written software-pipelined per-wave loop (next tile's loads in flight during the LDS / store phase); the compiler loop keeps w_out / w_pg / w_pe
# speedup vs baseline: 1.0061x; 1.0061x over previous
; #define LDS_WAIT() asm volatile("s_waitcnt lgkmcnt(0)" ::: "memory")
; __device__ __forceinline__ void p0_transpose_item(const float* W, int K, int N, bf16* WT, float* scr, int item, int lane, const float* scale, const float* cb, float* c1, float* c2) {
;     const int nblk = N / 64, kb = item / nblk, nb = item % nblk, k0 = 64 * kb, n0 = 64 * nb;
;     const int lr = lane >> 4, lc = (lane & 15) * 4;
;     f32x4 v[16];
; #pragma unroll
;     for (int i = 0; i < 16; ++i) v[i] = *(const f32x4*)(W + (size_t)(k0 + 4 * i + lr) * N + n0 + lc);
; #pragma unroll
;     for (int i = 0; i < 16; ++i) { const int kk = 4 * i + lr; f32x4 w = v[i]; if (scale) w = w * scale[k0 + kk]; float* d = scr + kk * 65 + lc; d[0] = w[0]; d[1] = w[1]; d[2] = w[2]; d[3] = w[3]; }
;     LDS_WAIT(); asm volatile("" ::: "memory");
.LBB0_17:
	s_cmp_lt_i32 s22, 1
	s_cselect_b64 s[0:1], -1, 0
	s_cmp_gt_i32 s23, 0
	s_cselect_b64 s[2:3], -1, 0
	s_and_b64 s[0:1], s[0:1], s[2:3]
	s_andn2_b64 vcc, exec, s[0:1]
	s_cbranch_vccnz .LBB0_130
	s_cmpk_lg_i32 s86, 0x100
	s_cbranch_scc1 .Lp0c_skip
	v_readfirstlane_b32 s50, v252
	s_lshr_b32 s50, s50, 6
	s_lshl_b32 s44, s96, 3
	s_add_i32 s44, s44, s50
	v_readlane_b32 s52, v253, 6
	v_readlane_b32 s53, v253, 7
	s_mul_i32 s45, s50, 0x4100
	s_add_u32 s54, s20, 0x200000
	s_addc_u32 s55, s21, 0
	v_and_b32_e32 v184, 63, v252
	v_lshrrev_b32_e32 v185, 4, v184
	v_and_b32_e32 v186, 15, v184
	v_mul_u32_u24_e32 v187, 0x7800, v185
	v_lshl_add_u32 v136, v186, 4, v187
	v_mul_u32_u24_e32 v187, 0x104, v185
	v_lshl_add_u32 v187, v186, 4, v187
	v_add_u32_e32 v152, s45, v187
	v_and_b32_e32 v188, 7, v184
	v_lshrrev_b32_e32 v189, 3, v184
	v_mul_u32_u24_e32 v190, 0x820, v188
	v_lshl_add_u32 v190, v189, 2, v190
	v_add_u32_e32 v174, s45, v190
	v_add_u32_e32 v175, 0x410, v174
	v_lshlrev_b32_e32 v191, 12, v189
	v_lshl_add_u32 v176, v188, 4, v191
	v_add_u32_e32 v137, 0x1e000, v136
	v_add_u32_e32 v153, 0x410, v152
	v_add_u32_e32 v138, 0x3c000, v136
	v_add_u32_e32 v154, 0x820, v152
	v_add_u32_e32 v139, 0x5a000, v136
	v_add_u32_e32 v155, 0xc30, v152
	v_add_u32_e32 v140, 0x78000, v136
	v_add_u32_e32 v156, 0x1040, v152
	v_add_u32_e32 v141, 0x96000, v136
	v_add_u32_e32 v157, 0x1450, v152
	v_add_u32_e32 v142, 0xb4000, v136
	v_add_u32_e32 v158, 0x1860, v152
	v_add_u32_e32 v143, 0xd2000, v136
	v_add_u32_e32 v159, 0x1c70, v152
	v_add_u32_e32 v144, 0xf0000, v136
	v_add_u32_e32 v160, 0x2080, v152
	v_add_u32_e32 v145, 0x10e000, v136
	v_add_u32_e32 v161, 0x2490, v152
	v_add_u32_e32 v146, 0x12c000, v136
	v_add_u32_e32 v162, 0x28a0, v152
	v_add_u32_e32 v147, 0x14a000, v136
	v_add_u32_e32 v163, 0x2cb0, v152
	v_add_u32_e32 v148, 0x168000, v136
	v_add_u32_e32 v164, 0x30c0, v152
	v_add_u32_e32 v149, 0x186000, v136
	v_add_u32_e32 v165, 0x34d0, v152
	v_add_u32_e32 v150, 0x1a4000, v136
	v_add_u32_e32 v166, 0x38e0, v152
	v_add_u32_e32 v151, 0x1c2000, v136
	v_add_u32_e32 v167, 0x3cf0, v152
	v_add_u32_e32 v177, 0x8000, v176
	v_add_u32_e32 v178, 0x10000, v176
	v_add_u32_e32 v179, 0x18000, v176
	v_add_u32_e32 v180, 0x20000, v176
	v_add_u32_e32 v181, 0x28000, v176
	v_add_u32_e32 v182, 0x30000, v176
	v_add_u32_e32 v183, 0x38000, v176
	s_lshr_b32 s40, s44, 3
	s_mul_hi_u32 s40, s40, 0x88888889
	s_lshr_b32 s40, s40, 3
	s_mul_i32 s41, s40, 0x78
	s_sub_i32 s41, s44, s41
	s_mul_i32 s42, s40, 0x1e0000
	s_lshl_b32 s43, s41, 8
	s_add_u32 s42, s42, s43
	s_add_u32 s56, s52, s42
	s_addc_u32 s57, s53, 0
	s_lshl_b32 s42, s41, 18
	s_lshl_b32 s43, s40, 7
	s_add_u32 s42, s42, s43
	s_add_u32 s58, s54, s42
	s_addc_u32 s59, s55, 0
	global_load_dwordx4 v[0:3], v136, s[56:57]
	global_load_dwordx4 v[4:7], v137, s[56:57]
	global_load_dwordx4 v[8:11], v138, s[56:57]
	global_load_dwordx4 v[12:15], v139, s[56:57]
	global_load_dwordx4 v[16:19], v140, s[56:57]
	global_load_dwordx4 v[20:23], v141, s[56:57]
	global_load_dwordx4 v[24:27], v142, s[56:57]
	global_load_dwordx4 v[28:31], v143, s[56:57]
	global_load_dwordx4 v[32:35], v144, s[56:57]
	global_load_dwordx4 v[36:39], v145, s[56:57]
	global_load_dwordx4 v[40:43], v146, s[56:57]
	global_load_dwordx4 v[44:47], v147, s[56:57]
	global_load_dwordx4 v[48:51], v148, s[56:57]
	global_load_dwordx4 v[52:55], v149, s[56:57]
	global_load_dwordx4 v[56:59], v150, s[56:57]
	global_load_dwordx4 v[60:63], v151, s[56:57]
	s_waitcnt vmcnt(0)
.Lp0c_loop:
	ds_write2_b32 v152, v0, v1 offset1:1
	ds_write2_b32 v152, v2, v3 offset0:2 offset1:3
	ds_write2_b32 v153, v4, v5 offset1:1
	ds_write2_b32 v153, v6, v7 offset0:2 offset1:3
	ds_write2_b32 v154, v8, v9 offset1:1
	ds_write2_b32 v154, v10, v11 offset0:2 offset1:3
	ds_write2_b32 v155, v12, v13 offset1:1
	ds_write2_b32 v155, v14, v15 offset0:2 offset1:3
	ds_write2_b32 v156, v16, v17 offset1:1
	ds_write2_b32 v156, v18, v19 offset0:2 offset1:3
	ds_write2_b32 v157, v20, v21 offset1:1
	ds_write2_b32 v157, v22, v23 offset0:2 offset1:3
	ds_write2_b32 v158, v24, v25 offset1:1
	ds_write2_b32 v158, v26, v27 offset0:2 offset1:3
	ds_write2_b32 v159, v28, v29 offset1:1
	ds_write2_b32 v159, v30, v31 offset0:2 offset1:3
	ds_write2_b32 v160, v32, v33 offset1:1
	ds_write2_b32 v160, v34, v35 offset0:2 offset1:3
	ds_write2_b32 v161, v36, v37 offset1:1
	ds_write2_b32 v161, v38, v39 offset0:2 offset1:3
	ds_write2_b32 v162, v40, v41 offset1:1
	ds_write2_b32 v162, v42, v43 offset0:2 offset1:3
	ds_write2_b32 v163, v44, v45 offset1:1
	ds_write2_b32 v163, v46, v47 offset0:2 offset1:3
	ds_write2_b32 v164, v48, v49 offset1:1
	ds_write2_b32 v164, v50, v51 offset0:2 offset1:3
	ds_write2_b32 v165, v52, v53 offset1:1
	ds_write2_b32 v165, v54, v55 offset0:2 offset1:3
	ds_write2_b32 v166, v56, v57 offset1:1
	ds_write2_b32 v166, v58, v59 offset0:2 offset1:3
	ds_write2_b32 v167, v60, v61 offset1:1
	ds_write2_b32 v167, v62, v63 offset0:2 offset1:3
	s_mov_b64 s[60:61], s[58:59]
	s_addk_i32 s44, 0x800
	s_mov_b32 s46, 0
	s_cmpk_gt_i32 s44, 0xeff
	s_cbranch_scc1 .Lp0c_nonext
	s_mov_b32 s46, 1
	s_lshr_b32 s40, s44, 3
	s_mul_hi_u32 s40, s40, 0x88888889
	s_lshr_b32 s40, s40, 3
	s_mul_i32 s41, s40, 0x78
	s_sub_i32 s41, s44, s41
	s_mul_i32 s42, s40, 0x1e0000
	s_lshl_b32 s43, s41, 8
	s_add_u32 s42, s42, s43
	s_add_u32 s56, s52, s42
	s_addc_u32 s57, s53, 0
	s_lshl_b32 s42, s41, 18
	s_lshl_b32 s43, s40, 7
	s_add_u32 s42, s42, s43
	s_add_u32 s58, s54, s42
	s_addc_u32 s59, s55, 0
	global_load_dwordx4 v[0:3], v136, s[56:57]
	global_load_dwordx4 v[4:7], v137, s[56:57]
	global_load_dwordx4 v[8:11], v138, s[56:57]
	global_load_dwordx4 v[12:15], v139, s[56:57]
	global_load_dwordx4 v[16:19], v140, s[56:57]
	global_load_dwordx4 v[20:23], v141, s[56:57]
	global_load_dwordx4 v[24:27], v142, s[56:57]
	global_load_dwordx4 v[28:31], v143, s[56:57]
	global_load_dwordx4 v[32:35], v144, s[56:57]
	global_load_dwordx4 v[36:39], v145, s[56:57]
	global_load_dwordx4 v[40:43], v146, s[56:57]
	global_load_dwordx4 v[44:47], v147, s[56:57]
	global_load_dwordx4 v[48:51], v148, s[56:57]
	global_load_dwordx4 v[52:55], v149, s[56:57]
	global_load_dwordx4 v[56:59], v150, s[56:57]
	global_load_dwordx4 v[60:63], v151, s[56:57]
; #define LDS_WAIT() asm volatile("s_waitcnt lgkmcnt(0)" ::: "memory")
; __device__ __forceinline__ unsigned pk2(float lo, float hi) { unsigned r; asm("v_cvt_pk_bf16_f32 %0, %1, %2" : "=v"(r) : "v"(lo), "v"(hi)); return r; }
; __device__ __forceinline__ void p0_transpose_item(const float* W, int K, int N, bf16* WT, float* scr, int item, int lane, const float* scale, const float* cb, float* c1, float* c2) {
;     ...
;     LDS_WAIT(); asm volatile("" ::: "memory");
;     const int c = lane & 7;
; #pragma unroll
;     for (int j = 0; j < 8; ++j) { const int n = (lane >> 3) + 8 * j; const float* sp = scr + (8 * c) * 65 + n;
;         v4u o; o.x = pk2(sp[0 * 65], sp[1 * 65]); o.y = pk2(sp[2 * 65], sp[3 * 65]); o.z = pk2(sp[4 * 65], sp[5 * 65]); o.w = pk2(sp[6 * 65], sp[7 * 65]);
;         *(v4u*)(WT + (size_t)(n0 + n) * K + k0 + 8 * c) = o; }
.Lp0c_nonext:
	s_waitcnt lgkmcnt(0)
	ds_read2_b32 v[64:65], v174 offset0:0 offset1:65
	ds_read2_b32 v[66:67], v174 offset0:130 offset1:195
	ds_read2_b32 v[68:69], v175 offset0:0 offset1:65
	ds_read2_b32 v[70:71], v175 offset0:130 offset1:195
	ds_read2_b32 v[72:73], v174 offset0:8 offset1:73
	ds_read2_b32 v[74:75], v174 offset0:138 offset1:203
	ds_read2_b32 v[76:77], v175 offset0:8 offset1:73
	ds_read2_b32 v[78:79], v175 offset0:138 offset1:203
	ds_read2_b32 v[80:81], v174 offset0:16 offset1:81
	ds_read2_b32 v[82:83], v174 offset0:146 offset1:211
	ds_read2_b32 v[84:85], v175 offset0:16 offset1:81
	ds_read2_b32 v[86:87], v175 offset0:146 offset1:211
	s_waitcnt lgkmcnt(8)
	v_cvt_pk_bf16_f32 v128, v64, v65
	v_cvt_pk_bf16_f32 v129, v66, v67
	v_cvt_pk_bf16_f32 v130, v68, v69
	v_cvt_pk_bf16_f32 v131, v70, v71
	global_store_dwordx4 v176, v[128:131], s[60:61]
	ds_read2_b32 v[88:89], v174 offset0:24 offset1:89
	ds_read2_b32 v[90:91], v174 offset0:154 offset1:219
	ds_read2_b32 v[92:93], v175 offset0:24 offset1:89
	ds_read2_b32 v[94:95], v175 offset0:154 offset1:219
	s_waitcnt lgkmcnt(8)
	v_cvt_pk_bf16_f32 v132, v72, v73
	v_cvt_pk_bf16_f32 v133, v74, v75
	v_cvt_pk_bf16_f32 v134, v76, v77
	v_cvt_pk_bf16_f32 v135, v78, v79
	global_store_dwordx4 v177, v[132:135], s[60:61]
	ds_read2_b32 v[96:97], v174 offset0:32 offset1:97
	ds_read2_b32 v[98:99], v174 offset0:162 offset1:227
	ds_read2_b32 v[100:101], v175 offset0:32 offset1:97
	ds_read2_b32 v[102:103], v175 offset0:162 offset1:227
	s_waitcnt lgkmcnt(8)
	v_cvt_pk_bf16_f32 v128, v80, v81
	v_cvt_pk_bf16_f32 v129, v82, v83
	v_cvt_pk_bf16_f32 v130, v84, v85
	v_cvt_pk_bf16_f32 v131, v86, v87
	global_store_dwordx4 v178, v[128:131], s[60:61]
	ds_read2_b32 v[104:105], v174 offset0:40 offset1:105
	ds_read2_b32 v[106:107], v174 offset0:170 offset1:235
	ds_read2_b32 v[108:109], v175 offset0:40 offset1:105
	ds_read2_b32 v[110:111], v175 offset0:170 offset1:235
	s_waitcnt lgkmcnt(8)
	v_cvt_pk_bf16_f32 v132, v88, v89
	v_cvt_pk_bf16_f32 v133, v90, v91
	v_cvt_pk_bf16_f32 v134, v92, v93
	v_cvt_pk_bf16_f32 v135, v94, v95
	global_store_dwordx4 v179, v[132:135], s[60:61]
	ds_read2_b32 v[112:113], v174 offset0:48 offset1:113
	ds_read2_b32 v[114:115], v174 offset0:178 offset1:243
	ds_read2_b32 v[116:117], v175 offset0:48 offset1:113
	ds_read2_b32 v[118:119], v175 offset0:178 offset1:243
	s_waitcnt lgkmcnt(8)
	v_cvt_pk_bf16_f32 v128, v96, v97
	v_cvt_pk_bf16_f32 v129, v98, v99
	v_cvt_pk_bf16_f32 v130, v100, v101
	v_cvt_pk_bf16_f32 v131, v102, v103
	global_store_dwordx4 v180, v[128:131], s[60:61]
	ds_read2_b32 v[120:121], v174 offset0:56 offset1:121
	ds_read2_b32 v[122:123], v174 offset0:186 offset1:251
	ds_read2_b32 v[124:125], v175 offset0:56 offset1:121
	ds_read2_b32 v[126:127], v175 offset0:186 offset1:251
	s_waitcnt lgkmcnt(8)
	v_cvt_pk_bf16_f32 v132, v104, v105
	v_cvt_pk_bf16_f32 v133, v106, v107
	v_cvt_pk_bf16_f32 v134, v108, v109
	v_cvt_pk_bf16_f32 v135, v110, v111
	global_store_dwordx4 v181, v[132:135], s[60:61]
	s_waitcnt lgkmcnt(4)
	v_cvt_pk_bf16_f32 v128, v112, v113
	v_cvt_pk_bf16_f32 v129, v114, v115
	v_cvt_pk_bf16_f32 v130, v116, v117
	v_cvt_pk_bf16_f32 v131, v118, v119
	global_store_dwordx4 v182, v[128:131], s[60:61]
	s_waitcnt lgkmcnt(0)
	v_cvt_pk_bf16_f32 v132, v120, v121
	v_cvt_pk_bf16_f32 v133, v122, v123
	v_cvt_pk_bf16_f32 v134, v124, v125
	v_cvt_pk_bf16_f32 v135, v126, v127
	global_store_dwordx4 v183, v[132:135], s[60:61]
	s_cmp_eq_u32 s46, 0
	s_cbranch_scc1 .Lp0c_skip
	s_waitcnt vmcnt(8)
	s_branch .Lp0c_loop
; __global__ void __launch_bounds__(512, 2) mk_fwd(Args args) {
;     ...
;     if (IN(0) && !(DIS&128)) { CONVERT_ITEMS(0, I_L); }
.Lp0c_skip:
	v_mov_b32_e32 v0, v252
	s_nop 0
	v_readfirstlane_b32 s2, v0
	s_ashr_i32 s4, s2, 6
	s_lshl_b32 s2, s96, 3
	s_add_i32 s24, s4, s2
	s_cmpk_lg_i32 s86, 0x100
	s_cbranch_scc1 .Lp0c_init_done
	s_movk_i32 s40, 0x1000
	s_cmpk_ge_i32 s24, 0x700
	s_cselect_b32 s40, 0x800, s40
	s_add_i32 s24, s24, s40
.Lp0c_init_done:
	s_mov_b64 s[2:3], s[20:21]
	s_cmpk_gt_i32 s24, 0x177f
	s_cbranch_scc1 .LBB0_67
	s_lshl_b32 s25, s86, 3
	s_add_u32 s26, s2, 0x200000
	s_addc_u32 s27, s3, 0
	s_add_u32 s28, s2, 0x3e00000
	s_addc_u32 s29, s3, 0
	s_add_u32 s30, s2, 0x4e00000
	s_addc_u32 s31, s3, 0
	s_add_u32 s34, s2, 0x5e00000
	s_addc_u32 s35, s3, 0
	s_add_u32 s37, s2, 0x10000
	s_addc_u32 s38, s3, 0
	v_and_b32_e32 v2, 63, v0
	v_bfe_u32 v80, v0, 4, 2
	v_bfe_u32 v82, v0, 3, 3
	v_lshlrev_b32_e32 v0, 3, v0
	s_add_u32 s39, s2, 0x14000
	s_mulk_i32 s4, 0x4100
	v_lshlrev_b32_e32 v68, 2, v2
	v_and_b32_e32 v0, 56, v0
	s_addc_u32 s40, s3, 0
	s_add_i32 s4, s4, 0
	v_and_b32_e32 v4, 60, v68
	v_mul_u32_u24_e32 v3, 0x104, v0
	v_lshlrev_b32_e32 v5, 2, v82
	v_readlane_b32 s44, v253, 18
	v_lshl_add_u32 v1, v4, 2, s4
	s_movk_i32 s2, 0x104
	v_add3_u32 v83, s4, v3, v5
	v_readlane_b32 s54, v253, 28
	v_readlane_b32 s55, v253, 29
	v_or_b32_e32 v3, 4, v80
	v_mov_b32_e32 v69, 0
	v_mad_u32_u24 v81, v80, s2, v1
	v_readlane_b32 s45, v253, 19
	v_readlane_b32 s46, v253, 20
	v_readlane_b32 s47, v253, 21
	v_readlane_b32 s48, v253, 22
	v_readlane_b32 s49, v253, 23
	v_readlane_b32 s50, v253, 24
	v_readlane_b32 s51, v253, 25
	v_readlane_b32 s52, v253, 26
	v_readlane_b32 s53, v253, 27
	v_readlane_b32 s56, v253, 30
	v_readlane_b32 s57, v253, 31
	v_readlane_b32 s58, v253, 32
	v_readlane_b32 s59, v253, 33
	s_cmp_lg_u64 s[54:55], 0
	v_mul_u32_u24_e32 v3, 0x104, v3
	v_or_b32_e32 v84, 8, v82
	v_or_b32_e32 v85, 16, v82
	v_or_b32_e32 v86, 24, v82
	v_or_b32_e32 v87, 32, v82
	v_or_b32_e32 v88, 40, v82
	v_or_b32_e32 v89, 48, v82
	v_or_b32_e32 v90, 56, v82
	s_cselect_b64 s[2:3], -1, 0
	v_add_u32_e32 v91, s4, v68
	v_lshl_add_u64 v[70:71], s[16:17], 0, v[68:69]
	s_mov_b32 s41, 0x8000
	s_mov_b32 s42, 0x10000
	s_mov_b32 s43, 0x18000
	s_mov_b32 s44, 0x20000
	s_mov_b32 s45, 0x28000
	s_mov_b32 s46, 0x30000
	s_mov_b32 s47, 0x38000
	s_mov_b32 s48, 0x40000
	s_mov_b32 s49, 0x48000
	s_mov_b32 s50, 0x50000
	s_mov_b32 s51, 0x58000
	s_mov_b32 s52, 0x60000
	s_mov_b32 s53, 0x68000
	s_mov_b32 s54, 0x70000
	s_mov_b32 s55, 0x78000
	v_add_u32_e32 v92, 0x410, v81
	v_add_u32_e32 v93, 0x418, v81
	v_add_u32_e32 v94, 0x820, v81
	v_add_u32_e32 v95, 0x828, v81
	v_add_u32_e32 v96, 0xc30, v81
	v_add_u32_e32 v97, 0xc38, v81
	v_add_u32_e32 v98, 0x1040, v81
	v_add_u32_e32 v99, 0x1048, v81
	v_add_u32_e32 v100, 0x1450, v81
	v_add_u32_e32 v101, 0x1458, v81
	v_add_u32_e32 v102, 0x1860, v81
	v_add_u32_e32 v103, 0x1868, v81
	v_add_u32_e32 v104, 0x1c70, v81
	v_add_u32_e32 v105, 0x1c78, v81
	v_add_u32_e32 v106, 0x2080, v81
	v_add_u32_e32 v107, 0x2088, v81
	v_add_u32_e32 v108, 0x2490, v81
	v_add_u32_e32 v109, 0x2498, v81
	v_add_u32_e32 v110, 0x28a0, v81
	v_add_u32_e32 v111, 0x28a8, v81
	v_add_u32_e32 v112, 0x2cb0, v81
	v_add_u32_e32 v113, 0x2cb8, v81
	v_add_u32_e32 v114, 0x30c0, v81
	v_add_u32_e32 v115, 0x30c8, v81
	v_add_u32_e32 v116, 0x34d0, v81
	v_add_u32_e32 v117, 0x34d8, v81
	v_add_u32_e32 v118, 0x38e0, v81
	v_add_u32_e32 v119, 0x38e8, v81
	v_add_u32_e32 v120, 0x3cf0, v81
	v_lshlrev_b32_e32 v72, 2, v2
	s_mov_b32 s56, 0x14a000
	s_mov_b32 s57, 0x168000
	s_mov_b32 s58, 0x186000
	s_mov_b32 s59, 0x1a4000
	s_mov_b32 s60, 0x1c2000
	v_lshlrev_b32_e32 v68, 2, v4
	v_add_u32_e32 v121, 0x3cf8, v81
	v_lshlrev_b32_e32 v74, 1, v0
	v_add_u32_e32 v122, v1, v3
	s_branch .LBB0_21
